# ssd1 (phase 9): static s_setprio 1 for waves 4-7
# speedup vs baseline: 1.0115x; 1.0115x over previous
.LBB0_159:
	s_andn2_b64 vcc, exec, s[0:1]
	s_cbranch_vccnz .LBB0_888
	s_cmp_lt_i32 s58, 8
	s_mov_b64 s[0:1], -1
	s_cbranch_scc1 .LBB0_289
	s_cmp_gt_i32 s58, 8
	s_cbranch_scc0 .LBB0_176
	v_readlane_b32 s0, v251, 36
	v_readlane_b32 s1, v251, 37
	v_mov_b32_e32 v0, v179
	s_andn2_b64 vcc, exec, s[0:1]
	s_cbranch_vccnz .LBB0_175
	v_ashrrev_i32_e32 v4, 8, v0
	v_add_u32_e32 v7, -1, v249
	v_and_b32_e32 v8, 64, v249
	v_lshlrev_b32_e32 v142, 5, v4
	v_readlane_b32 s0, v251, 30
	v_cmp_lt_i32_e32 vcc, v7, v8
	v_ashrrev_i32_e32 v143, 31, v142
	v_readlane_b32 s1, v251, 31
	v_cndmask_b32_e32 v7, v7, v249, vcc
	v_ashrrev_i32_e32 v2, 6, v0
	v_lshl_add_u64 v[146:147], v[142:143], 2, s[0:1]
	v_lshlrev_b32_e32 v143, 2, v7
	v_add_u32_e32 v7, -2, v249
	v_cmp_lt_i32_e32 vcc, v7, v8
	v_and_b32_e32 v145, 3, v2
	s_movk_i32 s0, 0x100
	v_cndmask_b32_e32 v7, v7, v249, vcc
	v_lshlrev_b32_e32 v149, 2, v7
	v_add_u32_e32 v7, -4, v249
	v_cmp_lt_i32_e32 vcc, v7, v8
	v_and_b32_e32 v5, 63, v0
	v_cmp_gt_u32_e64 s[52:53], s0, v0
	v_cndmask_b32_e32 v7, v7, v249, vcc
	v_lshlrev_b32_e32 v153, 2, v7
	v_add_u32_e32 v7, -8, v249
	v_cmp_lt_i32_e32 vcc, v7, v8
	v_readlane_b32 s0, v254, 5
	v_and_b32_e32 v148, 0x7f, v0
	v_cndmask_b32_e32 v7, v7, v249, vcc
	v_lshlrev_b32_e32 v155, 2, v7
	v_add_u32_e32 v7, -16, v249
	v_cmp_lt_i32_e32 vcc, v7, v8
	s_movk_i32 s1, 0x110
	v_and_b32_e32 v3, 31, v0
	v_cndmask_b32_e32 v7, v7, v249, vcc
	v_lshlrev_b32_e32 v157, 2, v7
	v_subrev_u32_e32 v7, 32, v249
	v_cmp_lt_i32_e32 vcc, v7, v8
	v_bfe_u32 v6, v0, 5, 1
	v_lshlrev_b32_e32 v144, 2, v5
	v_cndmask_b32_e32 v7, v7, v249, vcc
	v_lshlrev_b32_e32 v160, 2, v7
	v_bfrev_b32_e32 v7, 0.5
	v_lshl_or_b32 v161, v249, 2, v7
	v_lshlrev_b32_e32 v7, 10, v2
	v_ashrrev_i32_e32 v2, 2, v0
	v_and_b32_e32 v150, 0xffffffe0, v2
	v_add_u32_e32 v8, s0, v7
	v_lshlrev_b32_e32 v9, 4, v5
	v_cmp_eq_u32_e64 s[54:55], 0, v5
	v_lshlrev_b32_e32 v162, 1, v4
	v_lshlrev_b32_e32 v5, 1, v148
	v_lshl_add_u32 v163, v4, 7, -1
	v_lshlrev_b32_e32 v164, 6, v4
	v_mul_lo_u32 v4, v150, s1
	v_readlane_b32 s0, v254, 4
	v_lshl_or_b32 v10, v145, 6, v3
	v_lshl_or_b32 v2, v6, 9, v3
	v_add3_u32 v165, s0, v5, v4
	v_add3_u32 v166, s0, v4, v5
	v_lshlrev_b32_e32 v4, 4, v6
	v_mad_u32_u24 v184, v3, s1, v4
	v_mad_u32_u24 v185, v10, s1, v4
	v_readlane_b32 s0, v253, 36
	v_ashrrev_i32_e32 v151, 31, v150
	v_or_b32_e32 v152, 1, v144
	v_or_b32_e32 v154, 2, v144
	v_or_b32_e32 v156, 3, v144
	v_add_u32_e32 v167, 0x220, v165
	v_add_u32_e32 v168, 0x440, v165
	v_add_u32_e32 v169, 0x660, v165
	v_add_u32_e32 v170, 0x880, v165
	v_add_u32_e32 v171, 0xaa0, v165
	v_add_u32_e32 v172, 0xcc0, v165
	v_add_u32_e32 v173, 0xee0, v165
	v_add_u32_e32 v174, 0x1100, v165
	v_add_u32_e32 v175, 0x1320, v165
	v_add_u32_e32 v176, 0x1540, v165
	v_add_u32_e32 v177, 0x1760, v165
	v_add_u32_e32 v180, 0x1980, v165
	v_add_u32_e32 v181, 0x1ba0, v165
	v_add_u32_e32 v182, 0x1dc0, v165
	v_add_u32_e32 v183, 0x1fe0, v165
	s_movk_i32 s12, 0x110
	v_and_or_b32 v186, v0, 32, v7
	v_add_u32_e32 v187, v8, v9
	v_lshlrev_b32_e32 v158, 1, v2
	s_mov_b32 s8, s0
	v_readlane_b32 s1, v253, 37
	v_readfirstlane_b32 s2, v179
	s_cmp_ge_u32 s2, 0x100
	s_cbranch_scc0 .Lp9_np
	s_setprio 1
.Lp9_np:
	s_branch .LBB0_166
.LBB0_164:
	v_lshl_add_u32 v0, s9, 5, v164
	v_or_b32_e32 v130, v0, v159
	v_ashrrev_i32_e32 v131, 31, v130
	v_readlane_b32 s0, v251, 32
	v_lshlrev_b64 v[130:131], 14, v[130:131]
	v_readlane_b32 s1, v251, 33
	s_nop 1
	v_lshl_add_u64 v[130:131], s[0:1], 0, v[130:131]
